# static s_setprio 1 for waves 4-7 during the attention and GLA-scan phases (reset at phase exit), on top of pipelined census loads
# baseline (speedup 1.0000x reference)
; #define LAS __attribute__((address_space(3)))
; __device__ __forceinline__ void attn_phase(LAS unsigned char* lds, const bf16* qkv, const float* gq, const float* gk, const float* relb, bf16* ao, int tid, int lane, int w) {
;     ...
;     f32x4 gqa[4], gqb[4];
; #pragma unroll
;     for (int ks = 0; ks < 4; ++ks) {
;         gqa[ks] = *(const f32x4*)(gq + ks * 32 + g * 8) * *(const f32x4*)(gk + ks * 32 + g * 8) * (0.08838834764831845f * LOG2E);
;         gqb[ks] = *(const f32x4*)(gq + ks * 32 + g * 8 + 4) * *(const f32x4*)(gk + ks * 32 + g * 8 + 4) * (0.08838834764831845f * LOG2E); }
;     ...
;                     const LAS float* bp = (const LAS float*)(lds + BT) + (dchunk * 64 + qi - 4 * g + 12);
; #pragma unroll
;                     for (int kt = 0; kt < 4; ++kt)
; #pragma unroll
;                         for (int j = 0; j < 4; ++j) s[kt][j] += bp[51 - kt * 16 - j];
;                 } else {
;                     const int dbase = dchunk * 64 + qi - 4 * g + 63;
; #pragma unroll
;                     for (int kt = 0; kt < 4; ++kt)
; #pragma unroll
;                         for (int j = 0; j < 4; ++j) { int idx = dbase - kt * 16 - j; idx = idx < 0 ? 0 : (idx > 319 ? 319 : idx); s[kt][j] += *(const LAS float*)(lds + BT + idx * 4); }
.LBB0_329:
	v_readlane_b32 s4, v245, 38
	v_readlane_b32 s5, v245, 39
	s_andn2_b64 vcc, exec, s[4:5]
	s_cbranch_vccnz .LBB0_367
	v_lshlrev_b64 v[46:47], 2, v[100:101]
	s_waitcnt lgkmcnt(0)
	v_lshl_add_u64 v[54:55], s[24:25], 0, v[46:47]
	s_waitcnt vmcnt(4)
	v_lshl_add_u64 v[56:57], s[18:19], 0, v[46:47]
	global_load_dwordx4 v[38:41], v[54:55], off offset:384
	global_load_dwordx4 v[42:45], v[54:55], off offset:400
	global_load_dwordx4 v[46:49], v[56:57], off offset:384
	global_load_dwordx4 v[50:53], v[56:57], off offset:400
	s_mov_b32 s4, 0x3e0293ee
	s_add_u32 s44, s16, 0x16400000
	s_addc_u32 s45, s17, 0
	v_lshlrev_b32_e32 v150, 2, v0
	s_ashr_i32 s24, s2, 2
	s_cmp_eq_u32 s24, 0
	s_cbranch_scc1 .Lprio_attn_skip
	s_setprio 1
.Lprio_attn_skip:
	v_lshlrev_b32_e32 v0, 4, v0
	v_lshlrev_b32_e32 v37, 2, v149
	v_lshlrev_b32_e32 v148, 3, v36
	v_ashrrev_i32_e32 v151, 31, v150
	s_mov_b32 s25, -1
	s_add_i32 s26, s24, 8
	s_sub_i32 s27, -4, s24
	s_waitcnt vmcnt(1)
	v_pk_mul_f32 v[40:41], v[40:41], v[48:49]
	s_waitcnt vmcnt(0)
	v_pk_mul_f32 v[44:45], v[44:45], v[52:53]
	v_pk_mul_f32 v[42:43], v[42:43], v[50:51]
	v_pk_mul_f32 v[38:39], v[38:39], v[46:47]
	v_pk_mul_f32 v[104:105], v[44:45], s[4:5] op_sel_hi:[1,0]
	v_pk_mul_f32 v[106:107], v[42:43], s[4:5] op_sel_hi:[1,0]
	v_pk_mul_f32 v[108:109], v[40:41], s[4:5] op_sel_hi:[1,0]
	v_pk_mul_f32 v[110:111], v[38:39], s[4:5] op_sel_hi:[1,0]
	global_load_dwordx4 v[38:41], v[54:55], off offset:256
	global_load_dwordx4 v[42:45], v[54:55], off offset:272
	global_load_dwordx4 v[46:49], v[56:57], off offset:256
	global_load_dwordx4 v[50:53], v[56:57], off offset:272
	s_waitcnt vmcnt(1)
	v_pk_mul_f32 v[40:41], v[40:41], v[48:49]
	s_waitcnt vmcnt(0)
	v_pk_mul_f32 v[44:45], v[44:45], v[52:53]
	v_pk_mul_f32 v[42:43], v[42:43], v[50:51]
	v_pk_mul_f32 v[38:39], v[38:39], v[46:47]
	v_pk_mul_f32 v[112:113], v[44:45], s[4:5] op_sel_hi:[1,0]
	v_pk_mul_f32 v[114:115], v[42:43], s[4:5] op_sel_hi:[1,0]
	v_pk_mul_f32 v[116:117], v[40:41], s[4:5] op_sel_hi:[1,0]
	v_pk_mul_f32 v[118:119], v[38:39], s[4:5] op_sel_hi:[1,0]
	global_load_dwordx4 v[38:41], v[54:55], off offset:128
	global_load_dwordx4 v[42:45], v[54:55], off offset:144
	global_load_dwordx4 v[46:49], v[56:57], off offset:128
	global_load_dwordx4 v[50:53], v[56:57], off offset:144
	s_waitcnt vmcnt(1)
	v_pk_mul_f32 v[40:41], v[40:41], v[48:49]
	s_waitcnt vmcnt(0)
	v_pk_mul_f32 v[44:45], v[44:45], v[52:53]
	v_pk_mul_f32 v[42:43], v[42:43], v[50:51]
	v_pk_mul_f32 v[38:39], v[38:39], v[46:47]
	v_pk_mul_f32 v[120:121], v[44:45], s[4:5] op_sel_hi:[1,0]
	v_pk_mul_f32 v[122:123], v[42:43], s[4:5] op_sel_hi:[1,0]
	v_pk_mul_f32 v[124:125], v[40:41], s[4:5] op_sel_hi:[1,0]
	v_pk_mul_f32 v[126:127], v[38:39], s[4:5] op_sel_hi:[1,0]
	global_load_dwordx4 v[38:41], v[54:55], off
	global_load_dwordx4 v[42:45], v[54:55], off offset:16
	global_load_dwordx4 v[46:49], v[56:57], off
	global_load_dwordx4 v[50:53], v[56:57], off offset:16
	s_waitcnt vmcnt(1)
	v_pk_mul_f32 v[40:41], v[40:41], v[48:49]
	s_waitcnt vmcnt(0)
	v_pk_mul_f32 v[44:45], v[44:45], v[52:53]
	v_pk_mul_f32 v[42:43], v[42:43], v[50:51]
	v_pk_mul_f32 v[38:39], v[38:39], v[46:47]
	v_pk_mul_f32 v[128:129], v[44:45], s[4:5] op_sel_hi:[1,0]
	v_pk_mul_f32 v[142:143], v[42:43], s[4:5] op_sel_hi:[1,0]
	v_pk_mul_f32 v[144:145], v[40:41], s[4:5] op_sel_hi:[1,0]
	v_pk_mul_f32 v[146:147], v[38:39], s[4:5] op_sel_hi:[1,0]
	s_movk_i32 s4, 0x13f
	v_cmp_lt_i32_e32 vcc, s4, v149
	s_movk_i32 s4, 0x110
	v_mul_lo_u32 v103, v168, s4
	s_lshl_b32 s4, s2, 4
	s_and_b32 s4, s4, 48
	v_lshrrev_b32_e32 v41, 2, v2
	s_movk_i32 s5, 0x120
	v_or_b32_e32 v174, s4, v2
	v_and_b32_e32 v38, -16, v3
	v_or_b32_e32 v41, v150, v41
	v_lshlrev_b32_e32 v3, 3, v3
	v_add_u32_e32 v40, 0x13f, v174
	v_mul_lo_u32 v41, v41, s5
	v_and_b32_e32 v3, 24, v3
	v_add3_u32 v175, 0, v41, v3
	v_sub_u32_e32 v41, v40, v150
	v_xad_u32 v40, v150, -1, v40
	v_sub_u32_e32 v39, v174, v150
	v_med3_i32 v40, v40, 0, v210
	v_lshlrev_b32_e32 v178, 2, v40
	v_max_i32_e32 v40, 0xfffffec3, v39
	v_add_u32_e32 v40, 0x13d, v40
	v_min_u32_e32 v40, 0x13f, v40
	v_lshlrev_b32_e32 v179, 2, v40
	v_max_i32_e32 v40, 0xfffffec4, v39
	v_add_u32_e32 v40, 0x13c, v40
	v_min_u32_e32 v40, 0x13f, v40
	v_lshlrev_b32_e32 v180, 2, v40
	v_max_i32_e32 v40, 0xfffffed1, v39
	v_add_u32_e32 v40, 0x12f, v40
	v_min_u32_e32 v40, 0x13f, v40
	v_lshlrev_b32_e32 v181, 2, v40
	v_max_i32_e32 v40, 0xfffffed2, v39
	v_add_u32_e32 v40, 0x12e, v40
	v_min_u32_e32 v40, 0x13f, v40
	v_lshlrev_b32_e32 v182, 2, v40
	v_max_i32_e32 v40, 0xfffffed3, v39
	v_add_u32_e32 v40, 0x12d, v40
	v_min_u32_e32 v40, 0x13f, v40
	v_lshlrev_b32_e32 v183, 2, v40
	v_max_i32_e32 v40, 0xfffffed4, v39
	v_add_u32_e32 v40, 0x12c, v40
	v_min_u32_e32 v40, 0x13f, v40
	v_lshlrev_b32_e32 v184, 2, v40
	v_max_i32_e32 v40, 0xfffffee1, v39
	v_add_u32_e32 v40, 0x11f, v40
	v_min_u32_e32 v40, 0x13f, v40
	v_lshlrev_b32_e32 v185, 2, v40
	v_max_i32_e32 v40, 0xfffffee2, v39
	v_add_u32_e32 v40, 0x11e, v40
	v_min_u32_e32 v40, 0x13f, v40
	v_lshlrev_b32_e32 v186, 2, v40
	v_max_i32_e32 v40, 0xfffffee3, v39
	v_add_u32_e32 v40, 0x11d, v40
	v_min_u32_e32 v40, 0x13f, v40
	v_lshlrev_b32_e32 v187, 2, v40
	v_max_i32_e32 v40, 0xfffffee4, v39
	v_add_u32_e32 v40, 0x11c, v40
	v_min_u32_e32 v40, 0x13f, v40
	v_lshlrev_b32_e32 v188, 2, v40
	v_max_i32_e32 v40, 0xfffffef1, v39
	v_add_u32_e32 v40, 0x10f, v40
	v_mul_u32_u24_e32 v3, 0x110, v2
	v_min_u32_e32 v40, 0x13f, v40
	v_lshlrev_b32_e32 v189, 2, v40
	v_max_i32_e32 v40, 0xfffffef2, v39
	v_add3_u32 v193, 0, v38, v3
	v_lshl_or_b32 v3, s24, 6, v2
	s_and_b32 s2, s2, 3
	v_add_u32_e32 v40, 0x10e, v40
	v_or_b32_e32 v194, s4, v3
	s_lshl_b32 s4, s24, 8
	s_lshl_b32 s2, s2, 6
	v_min_u32_e32 v40, 0x13f, v40
	s_or_b32 s2, s4, s2
	v_add_u32_e32 v169, 0, v103
	v_lshl_add_u32 v176, v39, 2, s3
	v_lshlrev_b32_e32 v190, 2, v40
	v_max_i32_e32 v40, 0xfffffef3, v39
	v_max_i32_e32 v39, 0xfffffef4, v39
	v_lshl_or_b32 v2, v2, 2, s2
	v_lshl_add_u32 v172, v168, 4, v169
	v_add_u32_e32 v40, 0x10d, v40
	v_add_u32_e32 v39, 0x10c, v39
	v_sub_u32_e32 v0, v2, v0
	v_readlane_b32 s2, v244, 24
	v_mul_lo_u32 v171, v168, s5
	v_add_u32_e32 v36, 0x2400, v172
	v_med3_i32 v41, v41, 0, v210
	v_min_u32_e32 v40, 0x13f, v40
	v_min_u32_e32 v39, 0x13f, v39
	v_add_u32_e32 v195, s2, v0
	v_add_u32_e32 v0, 0, v37
	v_add_u32_e32 v170, 0x2200, v103
	v_add_u32_e32 v173, 0x2400, v171
	v_lshlrev_b32_e32 v177, 2, v41
	v_lshlrev_b32_e32 v191, 2, v40
	v_lshlrev_b32_e32 v192, 2, v39
	s_xor_b64 s[46:47], vcc, -1
	v_add_u32_e32 v196, 0x11800, v0
	v_add_u32_e32 v197, v36, v102
	s_mov_b32 s4, s6
	s_branch .LBB0_333

; __device__ __forceinline__ void attn_phase(LAS unsigned char* lds, const bf16* qkv, const float* gq, const float* gk, const float* relb, bf16* ao, int tid, int lane, int w) {
;     ...
;     for (int unit = blockIdx.x; unit < 2048; unit += gridDim.x) {
.LBB0_367:
	s_setprio 0
	s_mov_b64 s[16:17], 0

; #define LAS __attribute__((address_space(3)))
; __device__ __forceinline__ void gla_scan(LAS unsigned char* lds, const bf16* proj, const float* dec, const float* qk0, const float* ssq0, bf16* og, float* hssq, int tid, int lane, int w) {
;     ...
;     const int g = lane >> 4, i16 = lane & 15, dvt = w & 3, half = w >> 2;
;     for (int unit = blockIdx.x; unit < 256; unit += gridDim.x) {
;         const int xcd = unit & 7, uidx = unit >> 3, bh = xcd * 4 + (uidx >> 3), b = bh >> 2, h = bh & 3, js = uidx & 7;
;         f32x4 S[8];
; #pragma unroll
;         for (int i = 0; i < 8; ++i) S[i] = (f32x4){0.f, 0.f, 0.f, 0.f};
;         { float a00; f32x4 q4 = (f32x4){0.f, 0.f, 0.f, 0.f}, k4 = (f32x4){0.f, 0.f, 0.f, 0.f};
; #pragma unroll
;           for (int kq = 0; kq < 8; ++kq) { q4 = q4 + *(const f32x4*)(qk0 + (size_t)(kq * 8 + b) * 2048 + h * 256 + lane * 4); k4 = k4 + *(const f32x4*)(qk0 + (size_t)(kq * 8 + b) * 2048 + 1024 + h * 256 + lane * 4); }
;           const float r2 = 1.0f / (ssq0[b * 2048] * (1.0f / 2048.0f) + EPS);
;           a00 = wave_sum((q4[0] * k4[0] + q4[1] * k4[1]) + (q4[2] * k4[2] + q4[3] * k4[3])) * 0.0625f * r2;
;           if (tid == 0) *(LAS float*)(lds + DC + 1024) = a00; }
;         const int lrow = tid >> 5, lch = tid & 31, vrow = tid >> 3, vch = tid & 7;
;         const bf16* pq = proj + (size_t)(b * 2048 + lrow) * NPROJ + h * 256 + lch * 8;
;         const bf16* pv = proj + (size_t)(b * 2048 + vrow) * NPROJ + 2048 + h * 512 + js * 64 + vch * 8;
;         const float* pd = dec + (size_t)(b * 32) * 1024 + h * 256 + (tid & 255);
;         f32x4 ofin[2];
; #pragma unroll
;         for (int k = 0; k < 2; ++k) ofin[k] = (f32x4){0.f, 0.f, 0.f, 0.f};
;     ...
;         v4u rq[4], rk[4], rv; float rd;
; #pragma unroll
;         for (int i = 0; i < 4; ++i) { rq[i] = *(const v4u*)(pq + (size_t)(16 * i) * NPROJ); rk[i] = *(const v4u*)(pq + (size_t)(16 * i) * NPROJ + 1024); }
;         rv = __builtin_nontemporal_load((const v4u*)pv); rd = pd[0];
.LBB0_429:
	s_or_b64 exec, exec, s[16:17]
	s_waitcnt lgkmcnt(0)
	v_mov_b32_e32 v2, v202
	s_barrier
	s_mov_b64 s[16:17], s[72:73]
	v_readfirstlane_b32 s2, v2
	v_and_b32_e32 v0, 63, v2
	s_ashr_i32 s2, s2, 6
	s_cmp_lt_u32 s2, 4
	s_cbranch_scc1 .Lprio_scan_skip
	s_setprio 1
.Lprio_scan_skip:
	s_and_b64 vcc, exec, s[40:41]
	s_cbranch_vccnz .LBB0_481
	s_load_dwordx2 s[34:35], s[16:17], 0x80
	v_and_b32_e32 v4, 64, v208
	v_add_u32_e32 v4, 64, v4
	v_xor_b32_e32 v6, 1, v208
	v_cmp_lt_i32_e32 vcc, v6, v4
	s_waitcnt lgkmcnt(0)
	s_add_u32 s24, s34, 0xa400000
	s_addc_u32 s25, s35, 0
	s_add_u32 s77, s34, 0x100000
	s_addc_u32 s22, s35, 0
	s_add_u32 s23, s34, 0x200000
	s_addc_u32 s14, s35, 0
	s_add_u32 s26, s34, 0x16400000
	s_addc_u32 s27, s35, 0
	s_add_u32 s15, s34, 0x1a400000
	v_ashrrev_i32_e32 v5, 4, v0
	s_addc_u32 s80, s35, 0
	s_ashr_i32 s4, s2, 2
	v_cndmask_b32_e32 v6, v208, v6, vcc
	s_ashr_i32 s9, s2, 1
	v_and_b32_e32 v3, 15, v0
	s_and_b32 s5, s2, 3
	v_lshlrev_b32_e32 v97, 2, v6
	v_xor_b32_e32 v6, 2, v208
	s_movk_i32 s7, 0x100
	v_lshlrev_b32_e32 v11, 2, v5
	s_lshl_b32 s10, s2, 1
	s_lshl_b32 s11, s9, 4
	s_lshl_b32 s81, s4, 8
	v_lshlrev_b32_e32 v94, 2, v0
	v_cmp_lt_i32_e32 vcc, v6, v4
	v_cmp_gt_i32_e64 s[42:43], s7, v2
	s_lshl_b32 s7, s4, 5
	s_lshl_b32 s8, s5, 4
	s_and_b32 s10, s10, 2
	v_or_b32_e32 v12, s11, v3
	v_add_u32_e32 v15, s11, v11
	s_add_i32 s11, s81, 0
	v_cndmask_b32_e32 v6, v208, v6, vcc
	v_and_b32_e32 v13, -16, v0
	v_lshlrev_b32_e32 v5, 3, v5
	v_bfe_u32 v0, v0, 2, 2
	v_and_b32_e32 v17, 12, v94
	s_cmp_lt_u32 s2, 4
	v_lshlrev_b32_e32 v114, 2, v6
	v_xor_b32_e32 v6, 4, v208
	s_movk_i32 s12, 0x90
	v_or_b32_e32 v121, s8, v3
	s_movk_i32 s16, 0x210
	v_or_b32_e32 v0, v5, v0
	v_or_b32_e32 v18, s8, v17
	s_cselect_b64 s[46:47], -1, 0
	s_lshl_b32 s2, s4, 6
	v_readlane_b32 s8, v244, 26
	v_cmp_lt_i32_e32 vcc, v6, v4
	v_add_u32_e32 v16, s11, v5
	v_mul_lo_u32 v5, v0, s12
	s_add_i32 s2, s8, s2
	v_mul_lo_u32 v0, v0, s16
	v_lshlrev_b32_e32 v17, 1, v17
	v_cndmask_b32_e32 v6, v208, v6, vcc
	v_add_u32_e32 v19, s2, v13
	s_lshl_b32 s2, s4, 3
	v_add3_u32 v122, 0, v0, v17
	v_subrev_u32_e32 v0, s7, v11
	v_add_u32_e32 v124, s7, v11
	s_add_i32 s7, 0, 0x15000
	v_lshlrev_b32_e32 v115, 2, v6
	v_xor_b32_e32 v6, 8, v208
	s_cmp_le_i32 s10, s9
	v_cmp_lt_i32_e32 vcc, v6, v4
	s_cselect_b64 s[68:69], -1, 0
	s_cmp_lt_i32 s10, s9
	v_cndmask_b32_e32 v6, v208, v6, vcc
	s_cselect_b64 s[28:29], -1, 0
	s_lshl_b32 s90, s4, 9
	s_or_b32 s4, s2, 1
	v_lshlrev_b32_e32 v116, 2, v6
	v_xor_b32_e32 v6, 16, v208
	s_lshl_b32 s91, s4, 5
	s_lshl_b32 s72, s4, 6
	s_or_b32 s4, s2, 2
	v_cmp_lt_i32_e32 vcc, v6, v4
	s_lshl_b32 s73, s4, 5
	s_lshl_b32 s94, s4, 6
	s_or_b32 s4, s2, 3
	v_cndmask_b32_e32 v6, v208, v6, vcc
	s_lshl_b32 s95, s4, 5
	s_lshl_b32 s78, s4, 6
	s_or_b32 s4, s2, 4
	v_lshlrev_b32_e32 v117, 2, v6
	v_xor_b32_e32 v6, 32, v208
	s_lshl_b32 s79, s4, 5
	s_lshl_b32 s38, s4, 6
	s_or_b32 s4, s2, 5
	v_cmp_lt_i32_e32 vcc, v6, v4
	v_and_b32_e32 v7, 31, v2
	v_ashrrev_i32_e32 v120, 3, v2
	v_lshl_or_b32 v20, s10, 4, v3
	s_lshl_b32 s39, s4, 5
	s_lshl_b32 s92, s4, 6
	s_or_b32 s4, s2, 6
	s_or_b32 s2, s2, 7
	v_cndmask_b32_e32 v4, v208, v6, vcc
	v_cmp_eq_u32_e64 s[40:41], 0, v2
	v_ashrrev_i32_e32 v119, 5, v2
	v_and_b32_e32 v9, 7, v2
	v_and_b32_e32 v8, 0xff, v2
	v_lshlrev_b32_e32 v96, 4, v7
	v_mul_lo_u32 v10, v120, s12
	v_readlane_b32 s13, v244, 25
	v_lshlrev_b32_e32 v2, 2, v2
	v_mul_lo_u32 v12, v12, s16
	v_or_b32_e32 v23, 1, v15
	v_or_b32_e32 v24, 2, v15
	v_or_b32_e32 v25, 3, v15
	v_or_b32_e32 v26, 16, v20
	s_lshl_b32 s93, s4, 5
	s_lshl_b32 s98, s4, 6
	s_lshl_b32 s99, s2, 5
	s_lshl_b32 s4, s2, 6
	s_movk_i32 s2, 0x110
	v_lshlrev_b32_e32 v118, 2, v4
	v_lshlrev_b32_e32 v4, 3, v7
	v_lshlrev_b32_e32 v6, 3, v9
	v_add_u32_e32 v7, 0, v96
	v_add_u32_e32 v10, s13, v10
	v_lshlrev_b32_e32 v9, 4, v9
	v_cmp_eq_u32_e64 s[44:45], 0, v3
	v_add_u32_e32 v12, 0, v12
	v_add_u32_e32 v14, 0, v13
	v_add_u32_e32 v5, s13, v5
	v_lshlrev_b32_e32 v18, 1, v18
	v_readlane_b32 s11, v244, 27
	v_lshl_add_u32 v11, v121, 2, s7
	v_mul_lo_u32 v17, v119, s16
	v_mul_u32_u24_e32 v21, 0x210, v20
	v_mul_lo_u32 v22, v15, s12
	v_mul_u32_u24_e32 v27, 0x210, v3
	v_mul_u32_u24_e32 v3, 0x90, v3
	v_mul_lo_u32 v0, v0, s2
	v_mul_lo_u32 v28, v124, s2
	v_cmp_eq_u32_e64 s[50:51], 0, v20
	v_lshl_add_u32 v29, v20, 1, s8
	v_cmp_gt_i32_e64 s[52:53], v20, v15
	v_cmp_gt_i32_e64 s[54:55], v20, v23
	v_cmp_gt_i32_e64 s[56:57], v20, v24
	v_cmp_gt_i32_e64 s[58:59], v20, v25
	v_lshl_add_u32 v20, v26, 1, s8
	v_add_u32_e32 v2, 0, v2
	v_ashrrev_i32_e32 v95, 31, v94
	v_add_u32_e32 v123, s11, v13
	v_cmp_eq_u32_e64 s[48:49], 0, v15
	v_cmp_gt_i32_e64 s[60:61], v26, v15
	v_cmp_gt_i32_e64 s[62:63], v26, v23
	v_cmp_gt_i32_e64 s[64:65], v26, v24
	v_cmp_gt_i32_e64 s[66:67], v26, v25
	v_add_u32_e32 v125, 0x7c0, v124
	v_lshl_or_b32 v98, v8, 2, v214
	v_mov_b32_e32 v99, v1
	v_or_b32_e32 v100, 0xa4c1000, v9
	v_mov_b32_e32 v101, v1
	v_lshlrev_b32_e32 v102, 1, v4
	v_lshlrev_b32_e32 v104, 1, v6
	v_lshlrev_b32_e32 v126, 2, v8
	s_lshl_b32 s5, s5, 2
	v_add_u32_e32 v127, v7, v17
	v_add_u32_e32 v128, v10, v9
	v_add_u32_e32 v129, 0x19400, v2
	v_add_u32_e32 v142, v29, v22
	v_add_u32_e32 v143, v20, v22
	v_add_u32_e32 v144, v16, v27
	v_add_u32_e32 v145, v5, v18
	v_add_u32_e32 v146, v19, v3
	v_add_u32_e32 v147, v11, v0
	v_add_u32_e32 v148, v11, v28
	v_add_u32_e32 v149, v12, v13
	v_add_u32_e32 v150, v14, v21
	s_mov_b32 s2, s6
	s_branch .LBB0_432

; __device__ __forceinline__ void xcd_barrier(const XcdBarrier& b) {
;     asm volatile("s_waitcnt vmcnt(0)" ::: "memory");
;     __syncthreads();
;     if (threadIdx.x == 0) {
;         unsigned* bar = b.bar;
;         __builtin_amdgcn_s_waitcnt(0);
;         unsigned nloc = b.st[0], nx = b.st[1];
;         if (nloc == 0u) { xcd_barrier_complete(bar, b.x, nloc, nx); b.st[0] = nloc; b.st[1] = nx; }
.LBB0_481:
	s_setprio 0
	s_waitcnt vmcnt(0)
	s_barrier
	s_and_saveexec_b64 s[16:17], s[78:79]
	s_cbranch_execz .LBB0_533
	v_readlane_b32 s2, v244, 22
	s_waitcnt vmcnt(0) expcnt(0) lgkmcnt(0)
	s_nop 0
	v_mov_b32_e32 v0, s2
	ds_read_b32 v3, v0
	v_readlane_b32 s2, v244, 23
	s_waitcnt lgkmcnt(0)
	v_cmp_ne_u32_e32 vcc, 0, v3
	v_mov_b32_e32 v0, s2
	ds_read_b32 v2, v0
	s_cbranch_vccnz .LBB0_497
	s_mov_b32 s2, 1
	s_branch .LBB0_485
